# per-CU stagger (0-3us by CU index within XCD) at up-proj phase start to spread epilogue store bursts; plus SWA bias straight-line
# speedup vs baseline: 1.0021x; 1.0021x over previous
.LBB0_770:
	s_or_b64 exec, exec, s[6:7]
	s_mov_b32 s2, 0
	s_mov_b32 s0, 0
	s_mov_b32 s12, s1
	v_mov_b32_e32 v0, v195
	s_movk_i32 s3, 0x100
	s_waitcnt lgkmcnt(0)
	s_barrier
	v_readlane_b32 s100, v254, 56
	s_lshr_b32 s100, s100, 3
	s_and_b32 s100, s100, 3
.Lstag_p4:
	s_cmp_eq_u32 s100, 0
	s_cbranch_scc1 .Lstag_p4_done
	s_sleep 32
	s_sub_u32 s100, s100, 1
	s_branch .Lstag_p4
.Lstag_p4_done:
	s_nop 0
	v_cmp_gt_i32_e32 vcc, s3, v0
	s_and_saveexec_b64 s[6:7], vcc
	s_cbranch_execz .LBB0_779
	s_ashr_i32 s3, s0, 31
	s_add_u32 s0, s62, s0
	s_addc_u32 s3, s63, s3
	s_lshl_b64 s[4:5], s[4:5], 2
	s_add_u32 s4, s0, s4
	v_mov_b32_e32 v2, 0x20400
	s_addc_u32 s5, s3, s5
	v_lshl_add_u32 v2, v0, 2, v2
	s_mov_b64 s[8:9], s[88:89]
	s_branch .LBB0_774
